# dwait plus K-tile 1 prologue pieces issued with K-tile 0's
# baseline (speedup 1.0000x reference)
; #define PG8_STAGE(bufoff, gbase, voff) do { _Pragma("unroll") for (int _i = 0; _i < 2; ++_i) \
;         __builtin_amdgcn_global_load_lds((const unsigned*)((const char*)(gbase) + (voff)[_i]), (PG8_LAS unsigned*)(lds + (bufoff) + ldsw + _i * 8192), 16, 0, 0); } while (0)
; #define PG8_WAIT_V(n) asm volatile("s_waitcnt vmcnt(" #n ")" ::: "memory")
; #define PG8_BAR __builtin_amdgcn_s_barrier()
; template <class Epi, class Sched, bool ALIGN_EPI = false, bool SP2 = false>
; __device__ __forceinline__ void gemm_phase(PG8_LAS unsigned char* lds, const Gemm g, const Sched& S, const Epi& E) {
;     ...
;         PG8_STAGE(PG8_SB(1, 0), cB + kstep, voffB); PG8_STAGE(PG8_SA(1, 0), cA + kstep, voffA); PG8_STAGE(PG8_SB(1, 1), cB + hstep + kstep, voffB);
;         PG8_WAIT_V(6); PG8_BAR;
;     __device__ __forceinline__ void finish(f32x4 (&acc)[2][2][4][2], const Pre& p) const {
; #pragma unroll
;         for (int ai = 0; ai < 2; ++ai)
; #pragma unroll
;             for (int m = 0; m < 4; ++m)
; #pragma unroll
;                 for (int bj = 0; bj < 2; ++bj) { float f[8]; unpack8(p.v[ai][m][bj], f);
;                     acc[ai][bj][m][0] = (f32x4){f[0], f[1], f[2], f[3]} * inv_alpha; acc[ai][bj][m][1] = (f32x4){f[4], f[5], f[6], f[7]} * inv_alpha; }
;     }
.LBB0_1552:
	v_or_b32_e32 v142, s5, v64
	v_lshlrev_b32_e32 v65, 6, v142
	v_lshlrev_b32_e32 v74, 4, v134
	s_movk_i32 s5, 0x3c0
	v_lshlrev_b32_e32 v75, 2, v142
	v_readlane_b32 s6, v255, 14
	v_and_or_b32 v65, v65, s5, v74
	s_lshl_b32 s4, s4, 13
	v_and_b32_e32 v75, 32, v75
	v_readlane_b32 s7, v255, 15
	v_bitop3_b32 v151, v65, s4, v75 bitop3:0xde
	v_lshl_or_b32 v65, v64, 6, v74
	v_lshlrev_b32_e32 v64, 2, v64
	v_lshl_add_u64 v[66:67], s[6:7], 0, v[144:145]
	v_mov_b32_e32 v129, v145
	v_readlane_b32 s28, v253, 26
	s_lshl_b32 s4, s24, 12
	v_and_b32_e32 v64, 32, v64
	v_lshl_add_u64 v[68:69], s[6:7], 0, v[128:129]
	v_mov_b32_e32 v133, v145
	v_readlane_b32 s29, v253, 27
	v_bitop3_b32 v143, v65, s4, v64 bitop3:0xde
	s_add_i32 m0, s26, 0x18000
	v_lshl_add_u64 v[64:65], v[66:67], 0, s[94:95]
	v_lshl_add_u64 v[70:71], s[28:29], 0, v[132:133]
	v_mov_b32_e32 v131, v145
	global_load_lds_dwordx4 v[64:65], off
	v_lshl_add_u64 v[64:65], v[68:69], 0, s[94:95]
	s_add_i32 m0, s26, 0x1a000
	s_add_i32 s34, s26, 0x8000
	v_lshl_add_u64 v[72:73], s[28:29], 0, v[130:131]
	global_load_lds_dwordx4 v[64:65], off
	v_lshl_add_u64 v[64:65], v[70:71], 0, s[94:95]
	s_mov_b32 m0, s34
	s_add_i32 s35, s26, 0xa000
	v_readlane_b32 s4, v255, 16
	global_load_lds_dwordx4 v[64:65], off
	v_lshl_add_u64 v[64:65], v[72:73], 0, s[94:95]
	s_mov_b32 m0, s35
	v_readlane_b32 s5, v255, 17
	global_load_lds_dwordx4 v[64:65], off
	s_add_i32 m0, s26, 0x1c000
	v_lshl_add_u64 v[64:65], s[4:5], 0, v[144:145]
	global_load_lds_dwordx4 v[64:65], off
	v_lshl_add_u64 v[64:65], s[4:5], 0, v[128:129]
	s_add_i32 m0, s26, 0x1e000
	s_nop 0
	global_load_lds_dwordx4 v[64:65], off
	s_waitcnt vmcnt(8)
	s_barrier
	s_waitcnt vmcnt(6)
	s_barrier
	s_waitcnt vmcnt(6)
	v_lshlrev_b32_e32 v120, 16, v60
	v_and_b32_e32 v121, 0xffff0000, v60
	v_lshlrev_b32_e32 v122, 16, v61
	v_and_b32_e32 v123, 0xffff0000, v61
	v_lshlrev_b32_e32 v124, 16, v62
	v_and_b32_e32 v125, 0xffff0000, v62
	v_lshlrev_b32_e32 v126, 16, v63
	v_and_b32_e32 v127, 0xffff0000, v63
	v_lshlrev_b32_e32 v112, 16, v56
	v_and_b32_e32 v113, 0xffff0000, v56
	v_lshlrev_b32_e32 v114, 16, v57
	v_and_b32_e32 v115, 0xffff0000, v57
	v_lshlrev_b32_e32 v116, 16, v58
	v_and_b32_e32 v117, 0xffff0000, v58
	v_lshlrev_b32_e32 v118, 16, v59
	v_and_b32_e32 v119, 0xffff0000, v59
	v_lshlrev_b32_e32 v100, 16, v52
	v_and_b32_e32 v101, 0xffff0000, v52
	v_lshlrev_b32_e32 v102, 16, v53
	v_and_b32_e32 v103, 0xffff0000, v53
	v_lshlrev_b32_e32 v104, 16, v54
	v_and_b32_e32 v105, 0xffff0000, v54
	v_lshlrev_b32_e32 v106, 16, v55
	v_and_b32_e32 v107, 0xffff0000, v55
	v_lshlrev_b32_e32 v96, 16, v48
	v_and_b32_e32 v97, 0xffff0000, v48
	v_lshlrev_b32_e32 v98, 16, v49
	v_and_b32_e32 v99, 0xffff0000, v49
	v_lshlrev_b32_e32 v108, 16, v50
	v_and_b32_e32 v109, 0xffff0000, v50
	v_lshlrev_b32_e32 v110, 16, v51
	v_and_b32_e32 v111, 0xffff0000, v51
	v_lshlrev_b32_e32 v84, 16, v44
	v_and_b32_e32 v85, 0xffff0000, v44
	v_lshlrev_b32_e32 v86, 16, v45
	v_and_b32_e32 v87, 0xffff0000, v45
	v_lshlrev_b32_e32 v88, 16, v46
	v_and_b32_e32 v89, 0xffff0000, v46
	v_lshlrev_b32_e32 v90, 16, v47
	v_and_b32_e32 v91, 0xffff0000, v47
	v_lshlrev_b32_e32 v80, 16, v40
	v_and_b32_e32 v81, 0xffff0000, v40
	v_lshlrev_b32_e32 v82, 16, v41
	v_and_b32_e32 v83, 0xffff0000, v41
	v_lshlrev_b32_e32 v92, 16, v42
	v_and_b32_e32 v93, 0xffff0000, v42
	v_lshlrev_b32_e32 v94, 16, v43
	v_and_b32_e32 v95, 0xffff0000, v43
	v_lshlrev_b32_e32 v68, 16, v36
	v_and_b32_e32 v69, 0xffff0000, v36
	v_lshlrev_b32_e32 v70, 16, v37
	v_and_b32_e32 v71, 0xffff0000, v37
	v_lshlrev_b32_e32 v72, 16, v38
	v_and_b32_e32 v73, 0xffff0000, v38
	v_lshlrev_b32_e32 v74, 16, v39
	v_and_b32_e32 v75, 0xffff0000, v39
	v_lshlrev_b32_e32 v64, 16, v28
	v_and_b32_e32 v65, 0xffff0000, v28
	v_lshlrev_b32_e32 v66, 16, v29
	v_and_b32_e32 v67, 0xffff0000, v29
	v_lshlrev_b32_e32 v76, 16, v30
	v_and_b32_e32 v77, 0xffff0000, v30
	v_lshlrev_b32_e32 v78, 16, v31
	v_and_b32_e32 v79, 0xffff0000, v31
	v_lshlrev_b32_e32 v52, 16, v32
	v_and_b32_e32 v53, 0xffff0000, v32
	v_lshlrev_b32_e32 v54, 16, v33
	v_and_b32_e32 v55, 0xffff0000, v33
	v_lshlrev_b32_e32 v56, 16, v34
	v_and_b32_e32 v57, 0xffff0000, v34
	v_lshlrev_b32_e32 v58, 16, v35
	v_and_b32_e32 v59, 0xffff0000, v35
	v_lshlrev_b32_e32 v48, 16, v20
	v_and_b32_e32 v49, 0xffff0000, v20
	v_lshlrev_b32_e32 v50, 16, v21
	v_and_b32_e32 v51, 0xffff0000, v21
	v_lshlrev_b32_e32 v60, 16, v22
	v_and_b32_e32 v61, 0xffff0000, v22
	v_lshlrev_b32_e32 v62, 16, v23
	v_and_b32_e32 v63, 0xffff0000, v23
	v_lshlrev_b32_e32 v36, 16, v24
	v_and_b32_e32 v37, 0xffff0000, v24
	v_lshlrev_b32_e32 v38, 16, v25
	v_and_b32_e32 v39, 0xffff0000, v25
	v_lshlrev_b32_e32 v40, 16, v26
	v_and_b32_e32 v41, 0xffff0000, v26
	v_lshlrev_b32_e32 v42, 16, v27
	v_and_b32_e32 v43, 0xffff0000, v27
	v_lshlrev_b32_e32 v32, 16, v4
	v_and_b32_e32 v33, 0xffff0000, v4
	v_lshlrev_b32_e32 v34, 16, v5
	v_and_b32_e32 v35, 0xffff0000, v5
	v_lshlrev_b32_e32 v44, 16, v6
	v_and_b32_e32 v45, 0xffff0000, v6
	v_lshlrev_b32_e32 v46, 16, v7
	v_and_b32_e32 v47, 0xffff0000, v7
	v_lshlrev_b32_e32 v20, 16, v16
	v_and_b32_e32 v21, 0xffff0000, v16
	v_lshlrev_b32_e32 v22, 16, v17
	v_and_b32_e32 v23, 0xffff0000, v17
	v_lshlrev_b32_e32 v24, 16, v18
	v_and_b32_e32 v25, 0xffff0000, v18
	v_lshlrev_b32_e32 v26, 16, v19
	v_and_b32_e32 v27, 0xffff0000, v19
	v_lshlrev_b32_e32 v16, 16, v0
	v_and_b32_e32 v17, 0xffff0000, v0
	v_lshlrev_b32_e32 v18, 16, v1
	v_and_b32_e32 v19, 0xffff0000, v1
	v_lshlrev_b32_e32 v28, 16, v2
	v_and_b32_e32 v29, 0xffff0000, v2
	v_lshlrev_b32_e32 v30, 16, v3
	v_and_b32_e32 v31, 0xffff0000, v3
	v_lshlrev_b32_e32 v4, 16, v8
	v_and_b32_e32 v5, 0xffff0000, v8
	v_lshlrev_b32_e32 v6, 16, v9
	v_and_b32_e32 v7, 0xffff0000, v9
	v_lshlrev_b32_e32 v8, 16, v10
	v_and_b32_e32 v9, 0xffff0000, v10
	v_lshlrev_b32_e32 v10, 16, v11
	v_and_b32_e32 v11, 0xffff0000, v11
	v_lshlrev_b32_e32 v0, 16, v12
	v_and_b32_e32 v1, 0xffff0000, v12
	v_lshlrev_b32_e32 v2, 16, v13
	v_and_b32_e32 v3, 0xffff0000, v13
	v_lshlrev_b32_e32 v12, 16, v14
	v_and_b32_e32 v13, 0xffff0000, v14
	v_lshlrev_b32_e32 v14, 16, v15
	v_and_b32_e32 v15, 0xffff0000, v15
	v_cmp_eq_u32_e64 s[36:37], 0, v134
	v_lshlrev_b32_e32 v134, 14, v140
	v_and_b32_e32 v134, 0xffff8000, v134
	v_lshl_add_u32 v134, v139, 11, v134
	v_lshlrev_b32_e32 v139, 14, v136
	v_and_b32_e32 v139, 0xffff8000, v139
	v_or_b32_e32 v150, s1, v135
	v_and_b32_e32 v135, 1, v140
	v_lshl_add_u32 v137, v137, 11, v139
	v_and_b32_e32 v136, 1, v136
	s_cmpk_lt_u32 s0, 0x100
	v_lshl_or_b32 v134, v135, 6, v134
	v_lshl_or_b32 v136, v136, 6, v137
	v_readlane_b32 s0, v253, 30
	s_cselect_b64 s[42:43], -1, 0
	s_mov_b32 s50, 0
	v_lshl_add_u32 v134, v141, 1, v134
	v_mov_b32_e32 v135, v145
	v_lshl_add_u32 v136, v138, 1, v136
	v_mov_b32_e32 v137, v145
	v_add_u32_e32 v151, 0, v151
	s_mov_b32 s52, s0
	v_readlane_b32 s51, v253, 24
	v_readlane_b32 s1, v253, 31
	s_branch .LBB0_1555

; #define PG8_STAGE(bufoff, gbase, voff) do { _Pragma("unroll") for (int _i = 0; _i < 2; ++_i) \
;         __builtin_amdgcn_global_load_lds((const unsigned*)((const char*)(gbase) + (voff)[_i]), (PG8_LAS unsigned*)(lds + (bufoff) + ldsw + _i * 8192), 16, 0, 0); } while (0)
; #define PG8_WAIT_V(n) asm volatile("s_waitcnt vmcnt(" #n ")" ::: "memory")
; #define PG8_BAR __builtin_amdgcn_s_barrier()
; template <class Epi, class Sched, bool ALIGN_EPI = false, bool SP2 = false>
; __device__ __forceinline__ void gemm_phase(PG8_LAS unsigned char* lds, const Gemm g, const Sched& S, const Epi& E) {
;     ...
;         PG8_STAGE(PG8_SB(1, 0), cB + kstep, voffB); PG8_STAGE(PG8_SA(1, 0), cA + kstep, voffA); PG8_STAGE(PG8_SB(1, 1), cB + hstep + kstep, voffB);
;         PG8_WAIT_V(6); PG8_BAR;
;     __device__ __forceinline__ void finish(f32x4 (&acc)[2][2][4][2], const Pre& p) const {
; #pragma unroll
;         for (int ai = 0; ai < 2; ++ai)
; #pragma unroll
;             for (int m = 0; m < 4; ++m)
; #pragma unroll
;                 for (int bj = 0; bj < 2; ++bj) { float f[8]; unpack8(p.v[ai][m][bj], f);
;                     acc[ai][bj][m][0] = (f32x4){f[0], f[1], f[2], f[3]} * inv_alpha; acc[ai][bj][m][1] = (f32x4){f[4], f[5], f[6], f[7]} * inv_alpha; }
;     }
.LBB0_1886:
	v_or_b32_e32 v142, s7, v68
	v_lshlrev_b32_e32 v69, 6, v142
	v_lshlrev_b32_e32 v74, 4, v134
	s_movk_i32 s7, 0x3c0
	v_lshlrev_b32_e32 v75, 2, v142
	v_readlane_b32 s16, v253, 32
	v_and_or_b32 v69, v69, s7, v74
	s_lshl_b32 s6, s6, 13
	v_and_b32_e32 v75, 32, v75
	v_mov_b32_e32 v133, v145
	v_readlane_b32 s17, v253, 33
	v_bitop3_b32 v153, v69, s6, v75 bitop3:0xde
	v_lshl_or_b32 v69, v68, 6, v74
	v_lshlrev_b32_e32 v68, 2, v68
	s_add_i32 m0, s30, 0x18000
	v_lshl_add_u64 v[64:65], v[64:65], 0, s[94:95]
	v_lshl_add_u64 v[70:71], s[16:17], 0, v[132:133]
	v_mov_b32_e32 v131, v145
	s_lshl_b32 s6, s28, 12
	v_and_b32_e32 v68, 32, v68
	global_load_lds_dwordx4 v[64:65], off
	v_lshl_add_u64 v[64:65], v[66:67], 0, s[94:95]
	s_add_i32 m0, s30, 0x1a000
	s_add_i32 s50, s30, 0x8000
	s_add_i32 s51, s30, 0xa000
	v_lshl_add_u64 v[72:73], s[16:17], 0, v[130:131]
	v_bitop3_b32 v143, v69, s6, v68 bitop3:0xde
	global_load_lds_dwordx4 v[64:65], off
	v_lshl_add_u64 v[64:65], v[70:71], 0, s[94:95]
	s_mov_b32 m0, s50
	s_add_u32 s6, s4, 0xb0080
	global_load_lds_dwordx4 v[64:65], off
	v_lshl_add_u64 v[64:65], v[72:73], 0, s[94:95]
	s_mov_b32 m0, s51
	s_addc_u32 s7, s5, 0
	global_load_lds_dwordx4 v[64:65], off
	s_add_i32 m0, s30, 0x1c000
	v_lshl_add_u64 v[64:65], s[6:7], 0, v[144:145]
	global_load_lds_dwordx4 v[64:65], off
	v_lshl_add_u64 v[64:65], s[6:7], 0, v[128:129]
	s_add_i32 m0, s30, 0x1e000
	s_nop 0
	global_load_lds_dwordx4 v[64:65], off
	s_waitcnt vmcnt(8)
	s_barrier
	s_waitcnt vmcnt(6)
	s_barrier
	s_waitcnt vmcnt(6)
	v_lshlrev_b32_e32 v124, 16, v60
	v_and_b32_e32 v125, 0xffff0000, v60
	v_lshlrev_b32_e32 v126, 16, v61
	v_and_b32_e32 v127, 0xffff0000, v61
	v_lshlrev_b32_e32 v120, 16, v62
	v_and_b32_e32 v121, 0xffff0000, v62
	v_lshlrev_b32_e32 v122, 16, v63
	v_and_b32_e32 v123, 0xffff0000, v63
	v_lshlrev_b32_e32 v116, 16, v56
	v_and_b32_e32 v117, 0xffff0000, v56
	v_lshlrev_b32_e32 v118, 16, v57
	v_and_b32_e32 v119, 0xffff0000, v57
	v_lshlrev_b32_e32 v112, 16, v58
	v_and_b32_e32 v113, 0xffff0000, v58
	v_lshlrev_b32_e32 v114, 16, v59
	v_and_b32_e32 v115, 0xffff0000, v59
	v_lshlrev_b32_e32 v108, 16, v52
	v_and_b32_e32 v109, 0xffff0000, v52
	v_lshlrev_b32_e32 v110, 16, v53
	v_and_b32_e32 v111, 0xffff0000, v53
	v_lshlrev_b32_e32 v104, 16, v54
	v_and_b32_e32 v105, 0xffff0000, v54
	v_lshlrev_b32_e32 v106, 16, v55
	v_and_b32_e32 v107, 0xffff0000, v55
	v_lshlrev_b32_e32 v100, 16, v48
	v_and_b32_e32 v101, 0xffff0000, v48
	v_lshlrev_b32_e32 v102, 16, v49
	v_and_b32_e32 v103, 0xffff0000, v49
	v_lshlrev_b32_e32 v96, 16, v50
	v_and_b32_e32 v97, 0xffff0000, v50
	v_lshlrev_b32_e32 v98, 16, v51
	v_and_b32_e32 v99, 0xffff0000, v51
	v_lshlrev_b32_e32 v92, 16, v44
	v_and_b32_e32 v93, 0xffff0000, v44
	v_lshlrev_b32_e32 v94, 16, v45
	v_and_b32_e32 v95, 0xffff0000, v45
	v_lshlrev_b32_e32 v88, 16, v46
	v_and_b32_e32 v89, 0xffff0000, v46
	v_lshlrev_b32_e32 v90, 16, v47
	v_and_b32_e32 v91, 0xffff0000, v47
	v_lshlrev_b32_e32 v84, 16, v40
	v_and_b32_e32 v85, 0xffff0000, v40
	v_lshlrev_b32_e32 v86, 16, v41
	v_and_b32_e32 v87, 0xffff0000, v41
	v_lshlrev_b32_e32 v80, 16, v42
	v_and_b32_e32 v81, 0xffff0000, v42
	v_lshlrev_b32_e32 v82, 16, v43
	v_and_b32_e32 v83, 0xffff0000, v43
	v_lshlrev_b32_e32 v76, 16, v36
	v_and_b32_e32 v77, 0xffff0000, v36
	v_lshlrev_b32_e32 v78, 16, v37
	v_and_b32_e32 v79, 0xffff0000, v37
	v_lshlrev_b32_e32 v72, 16, v38
	v_and_b32_e32 v73, 0xffff0000, v38
	v_lshlrev_b32_e32 v74, 16, v39
	v_and_b32_e32 v75, 0xffff0000, v39
	v_lshlrev_b32_e32 v68, 16, v28
	v_and_b32_e32 v69, 0xffff0000, v28
	v_lshlrev_b32_e32 v70, 16, v29
	v_and_b32_e32 v71, 0xffff0000, v29
	v_lshlrev_b32_e32 v64, 16, v30
	v_and_b32_e32 v65, 0xffff0000, v30
	v_lshlrev_b32_e32 v66, 16, v31
	v_and_b32_e32 v67, 0xffff0000, v31
	v_lshlrev_b32_e32 v60, 16, v32
	v_and_b32_e32 v61, 0xffff0000, v32
	v_lshlrev_b32_e32 v62, 16, v33
	v_and_b32_e32 v63, 0xffff0000, v33
	v_lshlrev_b32_e32 v56, 16, v34
	v_and_b32_e32 v57, 0xffff0000, v34
	v_lshlrev_b32_e32 v58, 16, v35
	v_and_b32_e32 v59, 0xffff0000, v35
	v_lshlrev_b32_e32 v52, 16, v20
	v_and_b32_e32 v53, 0xffff0000, v20
	v_lshlrev_b32_e32 v54, 16, v21
	v_and_b32_e32 v55, 0xffff0000, v21
	v_lshlrev_b32_e32 v48, 16, v22
	v_and_b32_e32 v49, 0xffff0000, v22
	v_lshlrev_b32_e32 v50, 16, v23
	v_and_b32_e32 v51, 0xffff0000, v23
	v_lshlrev_b32_e32 v44, 16, v24
	v_and_b32_e32 v45, 0xffff0000, v24
	v_lshlrev_b32_e32 v46, 16, v25
	v_and_b32_e32 v47, 0xffff0000, v25
	v_lshlrev_b32_e32 v40, 16, v26
	v_and_b32_e32 v41, 0xffff0000, v26
	v_lshlrev_b32_e32 v42, 16, v27
	v_and_b32_e32 v43, 0xffff0000, v27
	v_lshlrev_b32_e32 v36, 16, v12
	v_and_b32_e32 v37, 0xffff0000, v12
	v_lshlrev_b32_e32 v38, 16, v13
	v_and_b32_e32 v39, 0xffff0000, v13
	v_lshlrev_b32_e32 v32, 16, v14
	v_and_b32_e32 v33, 0xffff0000, v14
	v_lshlrev_b32_e32 v34, 16, v15
	v_and_b32_e32 v35, 0xffff0000, v15
	v_lshlrev_b32_e32 v28, 16, v16
	v_and_b32_e32 v29, 0xffff0000, v16
	v_lshlrev_b32_e32 v30, 16, v17
	v_and_b32_e32 v31, 0xffff0000, v17
	v_lshlrev_b32_e32 v24, 16, v18
	v_and_b32_e32 v25, 0xffff0000, v18
	v_lshlrev_b32_e32 v26, 16, v19
	v_and_b32_e32 v27, 0xffff0000, v19
	v_lshlrev_b32_e32 v20, 16, v4
	v_and_b32_e32 v21, 0xffff0000, v4
	v_lshlrev_b32_e32 v22, 16, v5
	v_and_b32_e32 v23, 0xffff0000, v5
	v_lshlrev_b32_e32 v16, 16, v6
	v_and_b32_e32 v17, 0xffff0000, v6
	v_lshlrev_b32_e32 v18, 16, v7
	v_and_b32_e32 v19, 0xffff0000, v7
	v_lshlrev_b32_e32 v12, 16, v8
	v_and_b32_e32 v13, 0xffff0000, v8
	v_lshlrev_b32_e32 v14, 16, v9
	v_and_b32_e32 v15, 0xffff0000, v9
	v_lshlrev_b32_e32 v8, 16, v10
	v_and_b32_e32 v9, 0xffff0000, v10
	v_lshlrev_b32_e32 v10, 16, v11
	v_and_b32_e32 v11, 0xffff0000, v11
	v_lshlrev_b32_e32 v4, 16, v0
	v_and_b32_e32 v5, 0xffff0000, v0
	v_lshlrev_b32_e32 v6, 16, v1
	v_and_b32_e32 v7, 0xffff0000, v1
	v_lshlrev_b32_e32 v0, 16, v2
	v_and_b32_e32 v1, 0xffff0000, v2
	v_lshlrev_b32_e32 v2, 16, v3
	v_and_b32_e32 v3, 0xffff0000, v3
	s_movk_i32 s7, 0xb00
	v_cmp_eq_u32_e64 s[36:37], 0, v134
	v_or_b32_e32 v150, s1, v135
	v_lshrrev_b32_e32 v135, 1, v141
	v_mul_lo_u32 v134, v140, s7
	s_mov_b32 s6, 0xb000
	v_lshrrev_b32_e32 v140, 1, v136
	v_mul_lo_u32 v136, v137, s7
	s_cmpk_lt_u32 s0, 0x100
	v_mad_u64_u32 v[134:135], s[0:1], v135, s6, v[134:135]
	v_mad_u64_u32 v[136:137], s[0:1], v140, s6, v[136:137]
	v_or_b32_e32 v134, v134, v151
	v_or_b32_e32 v136, v136, v138
	v_add_lshl_u32 v134, v134, v152, 1
	v_mov_b32_e32 v135, v145
	s_mov_b64 s[18:19], 0xb0080
	v_add_lshl_u32 v136, v136, v139, 1
	v_mov_b32_e32 v137, v145
	v_readlane_b32 s0, v253, 30
	s_cselect_b64 s[46:47], -1, 0
	s_mov_b32 s52, 0
	v_lshl_add_u64 v[134:135], v[134:135], 0, s[18:19]
	v_lshl_add_u64 v[136:137], v[136:137], 0, s[18:19]
	v_add_u32_e32 v151, 0, v153
	s_mov_b32 s56, s0
	v_readlane_b32 s55, v253, 24
	s_mov_b64 s[6:7], s[16:17]
	v_readlane_b32 s1, v253, 31
	s_branch .LBB0_1889
